# tile-index division fast path when the row-tile group is a full 8 (shift/mask instead of float reciprocal division)
# speedup vs baseline: 1.0640x; 1.0005x over previous
.LBB0_247:
	s_ashr_i32 s12, s16, 3
	s_add_i32 s12, s43, s12
	s_abs_i32 s16, s12
	s_mul_hi_u32 s17, s16, s25
	s_mul_i32 s43, s17, s23
	s_sub_i32 s16, s16, s43
	s_ashr_i32 s13, s12, 31
	s_add_i32 s43, s17, 1
	s_sub_i32 s44, s16, s23
	s_cmp_ge_u32 s16, s23
	s_cselect_b32 s17, s43, s17
	s_cselect_b32 s16, s44, s16
	s_add_i32 s43, s17, 1
	s_cmp_ge_u32 s16, s23
	s_cselect_b32 s16, s43, s17
	s_xor_b32 s16, s16, s13
	s_sub_i32 s13, s16, s13
	s_lshl_b32 s16, s13, 3
	s_sub_i32 s17, s53, s16
	s_min_i32 s17, s17, 8
	s_mul_i32 s13, s13, s23
	s_sub_i32 s12, s12, s13
	s_cmp_eq_u32 s17, 8
	s_cbranch_scc0 .Ldivslow_7
	s_lshr_b32 s43, s12, 3
	s_and_b32 s12, s12, 7
	s_add_i32 s44, s12, s16
	s_branch .LBB0_248
.Ldivslow_7:
	s_abs_i32 s43, s17
	v_cvt_f32_u32_e32 v2, s43
	s_sub_i32 s47, 0, s43
	v_rcp_iflag_f32_e32 v2, v2
	s_abs_i32 s13, s12
	s_xor_b32 s44, s12, s17
	s_ashr_i32 s44, s44, 31
	v_mul_f32_e32 v2, 0x4f7ffffe, v2
	v_cvt_u32_f32_e32 v2, v2
	s_nop 0
	v_readfirstlane_b32 s48, v2
	s_mul_i32 s47, s47, s48
	s_mul_hi_u32 s47, s48, s47
	s_add_i32 s48, s48, s47
	s_mul_hi_u32 s47, s13, s48
	s_mul_i32 s48, s47, s43
	s_sub_i32 s13, s13, s48
	s_add_i32 s48, s47, 1
	s_sub_i32 s49, s13, s43
	s_cmp_ge_u32 s13, s43
	s_cselect_b32 s47, s48, s47
	s_cselect_b32 s13, s49, s13
	s_add_i32 s48, s47, 1
	s_cmp_ge_u32 s13, s43
	s_cselect_b32 s13, s48, s47
	s_xor_b32 s13, s13, s44
	s_sub_i32 s43, s13, s44
	s_mul_i32 s13, s43, s17
	s_sub_i32 s12, s12, s13
	s_add_i32 s44, s12, s16

.LBB0_276:
	s_ashr_i32 s12, s16, 3
	s_add_i32 s12, s20, s12
	s_abs_i32 s16, s12
	s_mul_hi_u32 s17, s16, s66
	s_mul_i32 s20, s17, s48
	s_sub_i32 s16, s16, s20
	s_ashr_i32 s13, s12, 31
	s_add_i32 s20, s17, 1
	s_sub_i32 s21, s16, s48
	s_cmp_ge_u32 s16, s48
	s_cselect_b32 s17, s20, s17
	s_cselect_b32 s16, s21, s16
	s_add_i32 s20, s17, 1
	s_cmp_ge_u32 s16, s48
	s_cselect_b32 s16, s20, s17
	s_xor_b32 s16, s16, s13
	s_sub_i32 s13, s16, s13
	s_lshl_b32 s16, s13, 3
	s_sub_i32 s17, s53, s16
	s_min_i32 s17, s17, 8
	s_mul_i32 s13, s13, s48
	s_sub_i32 s12, s12, s13
	s_cmp_eq_u32 s17, 8
	s_cbranch_scc0 .Ldivslow_6
	s_lshr_b32 s69, s12, 3
	s_and_b32 s12, s12, 7
	s_add_i32 s27, s12, s16
	s_branch .LBB0_277
.Ldivslow_6:
	s_abs_i32 s20, s17
	v_cvt_f32_u32_e32 v2, s20
	s_sub_i32 s22, 0, s20
	v_rcp_iflag_f32_e32 v2, v2
	s_abs_i32 s13, s12
	s_xor_b32 s21, s12, s17
	s_ashr_i32 s21, s21, 31
	v_mul_f32_e32 v2, 0x4f7ffffe, v2
	v_cvt_u32_f32_e32 v2, v2
	s_nop 0
	v_readfirstlane_b32 s23, v2
	s_mul_i32 s22, s22, s23
	s_mul_hi_u32 s22, s23, s22
	s_add_i32 s23, s23, s22
	s_mul_hi_u32 s22, s13, s23
	s_mul_i32 s23, s22, s20
	s_sub_i32 s13, s13, s23
	s_add_i32 s23, s22, 1
	s_sub_i32 s24, s13, s20
	s_cmp_ge_u32 s13, s20
	s_cselect_b32 s22, s23, s22
	s_cselect_b32 s13, s24, s13
	s_add_i32 s23, s22, 1
	s_cmp_ge_u32 s13, s20
	s_cselect_b32 s13, s23, s22
	s_xor_b32 s13, s13, s21
	s_sub_i32 s69, s13, s21
	s_mul_i32 s13, s69, s17
	s_sub_i32 s12, s12, s13
	s_add_i32 s27, s12, s16

.LBB0_341:
	s_ashr_i32 s12, s15, 3
	s_add_i32 s12, s17, s12
	s_abs_i32 s15, s12
	s_mul_hi_u32 s16, s15, s68
	s_mul_i32 s17, s16, s96
	s_sub_i32 s15, s15, s17
	s_ashr_i32 s13, s12, 31
	s_add_i32 s17, s16, 1
	s_sub_i32 s18, s15, s96
	s_cmp_ge_u32 s15, s96
	s_cselect_b32 s16, s17, s16
	s_cselect_b32 s15, s18, s15
	s_add_i32 s17, s16, 1
	s_cmp_ge_u32 s15, s96
	s_cselect_b32 s15, s17, s16
	s_xor_b32 s15, s15, s13
	s_sub_i32 s13, s15, s13
	s_lshl_b32 s15, s13, 3
	s_sub_i32 s16, s53, s15
	s_min_i32 s16, s16, 8
	s_mul_i32 s13, s13, s96
	s_sub_i32 s12, s12, s13
	s_cmp_eq_u32 s16, 8
	s_cbranch_scc0 .Ldivslow_5
	s_lshr_b32 s66, s12, 3
	s_and_b32 s12, s12, 7
	s_add_i32 s65, s12, s15
	s_branch .LBB0_342
.Ldivslow_5:
	s_abs_i32 s17, s16
	v_cvt_f32_u32_e32 v2, s17
	s_sub_i32 s19, 0, s17
	v_rcp_iflag_f32_e32 v2, v2
	s_abs_i32 s13, s12
	s_xor_b32 s18, s12, s16
	s_ashr_i32 s18, s18, 31
	v_mul_f32_e32 v2, 0x4f7ffffe, v2
	v_cvt_u32_f32_e32 v2, v2
	s_nop 0
	v_readfirstlane_b32 s20, v2
	s_mul_i32 s19, s19, s20
	s_mul_hi_u32 s19, s20, s19
	s_add_i32 s20, s20, s19
	s_mul_hi_u32 s19, s13, s20
	s_mul_i32 s20, s19, s17
	s_sub_i32 s13, s13, s20
	s_add_i32 s20, s19, 1
	s_sub_i32 s21, s13, s17
	s_cmp_ge_u32 s13, s17
	s_cselect_b32 s19, s20, s19
	s_cselect_b32 s13, s21, s13
	s_add_i32 s20, s19, 1
	s_cmp_ge_u32 s13, s17
	s_cselect_b32 s13, s20, s19
	s_xor_b32 s13, s13, s18
	s_sub_i32 s66, s13, s18
	s_mul_i32 s13, s66, s16
	s_sub_i32 s12, s12, s13
	s_add_i32 s65, s12, s15

.LBB0_658:
	s_ashr_i32 s12, s18, 3
	s_add_i32 s12, s30, s12
	s_abs_i32 s18, s12
	s_mul_hi_u32 s19, s18, s27
	s_mul_i32 s30, s19, s26
	s_sub_i32 s18, s18, s30
	s_ashr_i32 s13, s12, 31
	s_add_i32 s30, s19, 1
	s_sub_i32 s46, s18, s26
	s_cmp_ge_u32 s18, s26
	s_cselect_b32 s19, s30, s19
	s_cselect_b32 s18, s46, s18
	s_add_i32 s30, s19, 1
	s_cmp_ge_u32 s18, s26
	s_cselect_b32 s18, s30, s19
	s_xor_b32 s18, s18, s13
	s_sub_i32 s13, s18, s13
	s_lshl_b32 s18, s13, 3
	s_sub_i32 s19, s53, s18
	s_min_i32 s19, s19, 8
	s_mul_i32 s13, s13, s26
	s_sub_i32 s12, s12, s13
	s_cmp_eq_u32 s19, 8
	s_cbranch_scc0 .Ldivslow_4
	s_lshr_b32 s46, s12, 3
	s_and_b32 s12, s12, 7
	s_add_i32 s30, s12, s18
	s_branch .LBB0_659
.Ldivslow_4:
	s_abs_i32 s30, s19
	v_cvt_f32_u32_e32 v2, s30
	s_sub_i32 s49, 0, s30
	v_rcp_iflag_f32_e32 v2, v2
	s_abs_i32 s13, s12
	s_xor_b32 s46, s12, s19
	s_ashr_i32 s46, s46, 31
	v_mul_f32_e32 v2, 0x4f7ffffe, v2
	v_cvt_u32_f32_e32 v2, v2
	s_nop 0
	v_readfirstlane_b32 s65, v2
	s_mul_i32 s49, s49, s65
	s_mul_hi_u32 s49, s65, s49
	s_add_i32 s65, s65, s49
	s_mul_hi_u32 s49, s13, s65
	s_mul_i32 s65, s49, s30
	s_sub_i32 s13, s13, s65
	s_add_i32 s65, s49, 1
	s_sub_i32 s66, s13, s30
	s_cmp_ge_u32 s13, s30
	s_cselect_b32 s49, s65, s49
	s_cselect_b32 s13, s66, s13
	s_add_i32 s65, s49, 1
	s_cmp_ge_u32 s13, s30
	s_cselect_b32 s13, s65, s49
	s_xor_b32 s13, s13, s46
	s_sub_i32 s46, s13, s46
	s_mul_i32 s13, s46, s19
	s_sub_i32 s12, s12, s13
	s_add_i32 s30, s12, s18

.LBB0_692:
	s_ashr_i32 s3, s3, 3
	s_add_i32 s3, s19, s3
	s_abs_i32 s13, s3
	s_mul_hi_u32 s18, s13, s44
	s_mul_i32 s19, s18, s42
	s_sub_i32 s13, s13, s19
	s_ashr_i32 s12, s3, 31
	s_add_i32 s19, s18, 1
	s_sub_i32 s45, s13, s42
	s_cmp_ge_u32 s13, s42
	s_cselect_b32 s18, s19, s18
	s_cselect_b32 s13, s45, s13
	s_add_i32 s19, s18, 1
	s_cmp_ge_u32 s13, s42
	s_cselect_b32 s13, s19, s18
	s_xor_b32 s13, s13, s12
	s_sub_i32 s12, s13, s12
	s_lshl_b32 s13, s12, 3
	s_sub_i32 s18, s53, s13
	s_min_i32 s18, s18, 8
	s_mul_i32 s12, s12, s42
	s_sub_i32 s12, s3, s12
	s_cmp_eq_u32 s18, 8
	s_cbranch_scc0 .Ldivslow_3
	s_lshr_b32 s3, s12, 3
	s_and_b32 s12, s12, 7
	s_add_i32 s45, s12, s13
	s_branch .LBB0_693
.Ldivslow_3:
	s_abs_i32 s19, s18
	v_cvt_f32_u32_e32 v2, s19
	s_sub_i32 s48, 0, s19
	v_rcp_iflag_f32_e32 v2, v2
	s_abs_i32 s3, s12
	s_xor_b32 s45, s12, s18
	s_ashr_i32 s45, s45, 31
	v_mul_f32_e32 v2, 0x4f7ffffe, v2
	v_cvt_u32_f32_e32 v2, v2
	s_nop 0
	v_readfirstlane_b32 s49, v2
	s_mul_i32 s48, s48, s49
	s_mul_hi_u32 s48, s49, s48
	s_add_i32 s49, s49, s48
	s_mul_hi_u32 s48, s3, s49
	s_mul_i32 s49, s48, s19
	s_sub_i32 s3, s3, s49
	s_add_i32 s49, s48, 1
	s_sub_i32 s65, s3, s19
	s_cmp_ge_u32 s3, s19
	s_cselect_b32 s48, s49, s48
	s_cselect_b32 s3, s65, s3
	s_add_i32 s49, s48, 1
	s_cmp_ge_u32 s3, s19
	s_cselect_b32 s3, s49, s48
	s_xor_b32 s3, s3, s45
	s_sub_i32 s3, s3, s45
	s_mul_i32 s18, s3, s18
	s_sub_i32 s12, s12, s18
	s_add_i32 s45, s12, s13

.LBB0_736:
	s_ashr_i32 s12, s22, 3
	s_add_i32 s12, s27, s12
	s_abs_i32 s22, s12
	s_mul_hi_u32 s23, s22, s68
	s_mul_i32 s27, s23, s48
	s_sub_i32 s22, s22, s27
	s_ashr_i32 s13, s12, 31
	s_add_i32 s27, s23, 1
	s_sub_i32 s65, s22, s48
	s_cmp_ge_u32 s22, s48
	s_cselect_b32 s23, s27, s23
	s_cselect_b32 s22, s65, s22
	s_add_i32 s27, s23, 1
	s_cmp_ge_u32 s22, s48
	s_cselect_b32 s22, s27, s23
	s_xor_b32 s22, s22, s13
	s_sub_i32 s13, s22, s13
	s_lshl_b32 s22, s13, 3
	s_sub_i32 s23, s53, s22
	s_min_i32 s23, s23, 8
	s_mul_i32 s13, s13, s48
	s_sub_i32 s12, s12, s13
	s_cmp_eq_u32 s23, 8
	s_cbranch_scc0 .Ldivslow_2
	s_lshr_b32 s69, s12, 3
	s_and_b32 s12, s12, 7
	s_add_i32 s27, s12, s22
	s_branch .LBB0_737
.Ldivslow_2:
	s_abs_i32 s27, s23
	v_cvt_f32_u32_e32 v2, s27
	s_sub_i32 s66, 0, s27
	v_rcp_iflag_f32_e32 v2, v2
	s_abs_i32 s13, s12
	s_xor_b32 s65, s12, s23
	s_ashr_i32 s65, s65, 31
	v_mul_f32_e32 v2, 0x4f7ffffe, v2
	v_cvt_u32_f32_e32 v2, v2
	s_nop 0
	v_readfirstlane_b32 s69, v2
	s_mul_i32 s66, s66, s69
	s_mul_hi_u32 s66, s69, s66
	s_add_i32 s69, s69, s66
	s_mul_hi_u32 s66, s13, s69
	s_mul_i32 s69, s66, s27
	s_sub_i32 s13, s13, s69
	s_add_i32 s69, s66, 1
	s_sub_i32 s70, s13, s27
	s_cmp_ge_u32 s13, s27
	s_cselect_b32 s66, s69, s66
	s_cselect_b32 s13, s70, s13
	s_add_i32 s69, s66, 1
	s_cmp_ge_u32 s13, s27
	s_cselect_b32 s13, s69, s66
	s_xor_b32 s13, s13, s65
	s_sub_i32 s69, s13, s65
	s_mul_i32 s13, s69, s23
	s_sub_i32 s12, s12, s13
	s_add_i32 s27, s12, s22

.LBB0_800:
	s_ashr_i32 s12, s22, 3
	s_add_i32 s12, s24, s12
	s_abs_i32 s22, s12
	s_mul_hi_u32 s23, s22, s68
	s_mul_i32 s24, s23, s63
	s_sub_i32 s22, s22, s24
	s_ashr_i32 s13, s12, 31
	s_add_i32 s24, s23, 1
	s_sub_i32 s25, s22, s63
	s_cmp_ge_u32 s22, s63
	s_cselect_b32 s23, s24, s23
	s_cselect_b32 s22, s25, s22
	s_add_i32 s24, s23, 1
	s_cmp_ge_u32 s22, s63
	s_cselect_b32 s22, s24, s23
	s_xor_b32 s22, s22, s13
	s_sub_i32 s13, s22, s13
	s_lshl_b32 s22, s13, 3
	s_sub_i32 s23, s53, s22
	s_min_i32 s23, s23, 8
	s_mul_i32 s13, s13, s63
	s_sub_i32 s12, s12, s13
	s_cmp_eq_u32 s23, 8
	s_cbranch_scc0 .Ldivslow_1
	s_lshr_b32 s70, s12, 3
	s_and_b32 s12, s12, 7
	s_add_i32 s31, s12, s22
	s_branch .LBB0_801
.Ldivslow_1:
	s_abs_i32 s24, s23
	v_cvt_f32_u32_e32 v2, s24
	s_sub_i32 s27, 0, s24
	v_rcp_iflag_f32_e32 v2, v2
	s_abs_i32 s13, s12
	s_xor_b32 s25, s12, s23
	s_ashr_i32 s25, s25, 31
	v_mul_f32_e32 v2, 0x4f7ffffe, v2
	v_cvt_u32_f32_e32 v2, v2
	s_nop 0
	v_readfirstlane_b32 s28, v2
	s_mul_i32 s27, s27, s28
	s_mul_hi_u32 s27, s28, s27
	s_add_i32 s28, s28, s27
	s_mul_hi_u32 s27, s13, s28
	s_mul_i32 s28, s27, s24
	s_sub_i32 s13, s13, s28
	s_add_i32 s28, s27, 1
	s_sub_i32 s29, s13, s24
	s_cmp_ge_u32 s13, s24
	s_cselect_b32 s27, s28, s27
	s_cselect_b32 s13, s29, s13
	s_add_i32 s28, s27, 1
	s_cmp_ge_u32 s13, s24
	s_cselect_b32 s13, s28, s27
	s_xor_b32 s13, s13, s25
	s_sub_i32 s70, s13, s25
	s_mul_i32 s13, s70, s23
	s_sub_i32 s12, s12, s13
	s_add_i32 s31, s12, s22
